# nt also on the q and gate bf16 stores of the layer-0 projection epilogue (read once by attention): Infinity Cache kept for the K/V tiles
# speedup vs baseline: 1.0183x; 1.0183x over previous
.LBB0_153:
	s_and_b64 s[10:11], s[10:11], exec
	s_mov_b32 s10, 0x4200000
	s_cselect_b32 s10, s10, 0x6300000
	s_cmp_gt_u32 s56, 1
	s_cselect_b32 s10, s10, 0x2100000
	s_add_u32 s10, s30, s10
	s_addc_u32 s11, s31, 0
	v_lshlrev_b32_e32 v174, 1, v142
	v_ashrrev_i32_e32 v209, 31, v208
	v_lshl_add_u64 v[138:139], s[10:11], 0, v[174:175]
	v_lshlrev_b64 v[140:141], 10, v[208:209]
	v_lshl_add_u64 v[140:141], v[138:139], 0, v[140:141]
	v_cvt_pk_bf16_f32 v130, v130, v131
	v_cvt_pk_bf16_f32 v131, v132, v133
	v_cvt_pk_bf16_f32 v132, v134, v135
	v_cvt_pk_bf16_f32 v133, v136, v137
	global_store_dwordx4 v[140:141], v[130:133], off nt
	s_andn2_b64 vcc, exec, s[12:13]
	s_nop 0
	v_cndmask_b32_e64 v130, 0, 1, s[12:13]
	v_cmp_ne_u32_e64 s[10:11], 1, v130
	s_mov_b64 s[12:13], -1
	s_cbranch_vccnz .LBB0_155
	v_mul_f32_e32 v130, 0xbfb8aa3b, v118
	v_mul_f32_e32 v131, 0xbfb8aa3b, v119
	v_mul_f32_e32 v132, 0xbfb8aa3b, v120
	v_mul_f32_e32 v133, 0xbfb8aa3b, v121
	v_mul_f32_e32 v134, 0xbfb8aa3b, v114
	v_mul_f32_e32 v135, 0xbfb8aa3b, v115
	v_mul_f32_e32 v136, 0xbfb8aa3b, v116
	v_mul_f32_e32 v137, 0xbfb8aa3b, v117
	v_exp_f32_e32 v130, v130
	v_exp_f32_e32 v131, v131
	v_exp_f32_e32 v132, v132
	v_exp_f32_e32 v133, v133
	v_exp_f32_e32 v134, v134
	v_exp_f32_e32 v135, v135
	v_exp_f32_e32 v136, v136
	v_exp_f32_e32 v137, v137
	v_add_f32_e32 v130, 1.0, v130
	v_add_f32_e32 v131, 1.0, v131
	v_add_f32_e32 v132, 1.0, v132
	v_add_f32_e32 v133, 1.0, v133
	v_add_f32_e32 v134, 1.0, v134
	v_add_f32_e32 v135, 1.0, v135
	v_add_f32_e32 v136, 1.0, v136
	v_add_f32_e32 v137, 1.0, v137
	v_rcp_f32_e32 v130, v130
	v_rcp_f32_e32 v131, v131
	v_rcp_f32_e32 v132, v132
	v_rcp_f32_e32 v133, v133
	v_rcp_f32_e32 v134, v134
	v_rcp_f32_e32 v136, v136
	v_rcp_f32_e32 v137, v137
	v_rcp_f32_e32 v135, v135
	v_pk_mul_f32 v[132:133], v[120:121], v[132:133]
	v_pk_mul_f32 v[130:131], v[118:119], v[130:131]
	v_pk_mul_f32 v[136:137], v[116:117], v[136:137]
	v_pk_mul_f32 v[134:135], v[114:115], v[134:135]
	s_mov_b64 s[12:13], 0

.LBB0_157:
	v_cvt_pk_bf16_f32 v130, v130, v131
	v_cvt_pk_bf16_f32 v131, v132, v133
	s_nop 0
	v_cvt_pk_bf16_f32 v132, v134, v135
	v_cvt_pk_bf16_f32 v133, v136, v137
	s_and_b64 vcc, exec, s[10:11]
	s_mov_b64 s[12:13], -1
	global_store_dwordx4 v[140:141], v[130:133], off offset:256 nt
	s_cbranch_vccnz .LBB0_159
	s_nop 0
	v_mul_f32_e32 v130, 0xbfb8aa3b, v110
	v_mul_f32_e32 v131, 0xbfb8aa3b, v111
	v_mul_f32_e32 v132, 0xbfb8aa3b, v112
	v_mul_f32_e32 v133, 0xbfb8aa3b, v113
	v_mul_f32_e32 v134, 0xbfb8aa3b, v106
	v_mul_f32_e32 v135, 0xbfb8aa3b, v107
	v_mul_f32_e32 v136, 0xbfb8aa3b, v108
	v_mul_f32_e32 v137, 0xbfb8aa3b, v109
	v_exp_f32_e32 v130, v130
	v_exp_f32_e32 v131, v131
	v_exp_f32_e32 v132, v132
	v_exp_f32_e32 v133, v133
	v_exp_f32_e32 v134, v134
	v_exp_f32_e32 v135, v135
	v_exp_f32_e32 v136, v136
	v_exp_f32_e32 v137, v137
	v_add_f32_e32 v130, 1.0, v130
	v_add_f32_e32 v131, 1.0, v131
	v_add_f32_e32 v132, 1.0, v132
	v_add_f32_e32 v133, 1.0, v133
	v_add_f32_e32 v134, 1.0, v134
	v_add_f32_e32 v135, 1.0, v135
	v_add_f32_e32 v136, 1.0, v136
	v_add_f32_e32 v137, 1.0, v137
	v_rcp_f32_e32 v130, v130
	v_rcp_f32_e32 v131, v131
	v_rcp_f32_e32 v132, v132
	v_rcp_f32_e32 v133, v133
	v_rcp_f32_e32 v134, v134
	v_rcp_f32_e32 v136, v136
	v_rcp_f32_e32 v137, v137
	v_rcp_f32_e32 v135, v135
	v_pk_mul_f32 v[132:133], v[112:113], v[132:133]
	v_pk_mul_f32 v[130:131], v[110:111], v[130:131]
	v_pk_mul_f32 v[136:137], v[108:109], v[136:137]
	v_pk_mul_f32 v[134:135], v[106:107], v[134:135]
	s_mov_b64 s[12:13], 0

.LBB0_161:
	v_or_b32_e32 v140, 16, v208
	v_ashrrev_i32_e32 v141, 31, v140
	v_lshlrev_b64 v[140:141], 10, v[140:141]
	v_lshl_add_u64 v[140:141], v[138:139], 0, v[140:141]
	v_cvt_pk_bf16_f32 v130, v130, v131
	v_cvt_pk_bf16_f32 v131, v132, v133
	v_cvt_pk_bf16_f32 v132, v134, v135
	v_cvt_pk_bf16_f32 v133, v136, v137
	s_and_b64 vcc, exec, s[10:11]
	s_mov_b64 s[12:13], -1
	global_store_dwordx4 v[140:141], v[130:133], off nt
	s_cbranch_vccnz .LBB0_163
	s_nop 0
	v_mul_f32_e32 v130, 0xbfb8aa3b, v102
	v_mul_f32_e32 v131, 0xbfb8aa3b, v103
	v_mul_f32_e32 v132, 0xbfb8aa3b, v104
	v_mul_f32_e32 v133, 0xbfb8aa3b, v105
	v_mul_f32_e32 v134, 0xbfb8aa3b, v98
	v_mul_f32_e32 v135, 0xbfb8aa3b, v99
	v_mul_f32_e32 v136, 0xbfb8aa3b, v100
	v_mul_f32_e32 v137, 0xbfb8aa3b, v101
	v_exp_f32_e32 v130, v130
	v_exp_f32_e32 v131, v131
	v_exp_f32_e32 v132, v132
	v_exp_f32_e32 v133, v133
	v_exp_f32_e32 v134, v134
	v_exp_f32_e32 v135, v135
	v_exp_f32_e32 v136, v136
	v_exp_f32_e32 v137, v137
	v_add_f32_e32 v130, 1.0, v130
	v_add_f32_e32 v131, 1.0, v131
	v_add_f32_e32 v132, 1.0, v132
	v_add_f32_e32 v133, 1.0, v133
	v_add_f32_e32 v134, 1.0, v134
	v_add_f32_e32 v135, 1.0, v135
	v_add_f32_e32 v136, 1.0, v136
	v_add_f32_e32 v137, 1.0, v137
	v_rcp_f32_e32 v130, v130
	v_rcp_f32_e32 v131, v131
	v_rcp_f32_e32 v132, v132
	v_rcp_f32_e32 v133, v133
	v_rcp_f32_e32 v134, v134
	v_rcp_f32_e32 v136, v136
	v_rcp_f32_e32 v137, v137
	v_rcp_f32_e32 v135, v135
	v_pk_mul_f32 v[132:133], v[104:105], v[132:133]
	v_pk_mul_f32 v[130:131], v[102:103], v[130:131]
	v_pk_mul_f32 v[136:137], v[100:101], v[136:137]
	v_pk_mul_f32 v[134:135], v[98:99], v[134:135]
	s_mov_b64 s[12:13], 0

.LBB0_165:
	v_cvt_pk_bf16_f32 v130, v130, v131
	v_cvt_pk_bf16_f32 v131, v132, v133
	s_nop 0
	v_cvt_pk_bf16_f32 v132, v134, v135
	v_cvt_pk_bf16_f32 v133, v136, v137
	s_and_b64 vcc, exec, s[10:11]
	s_mov_b64 s[12:13], -1
	global_store_dwordx4 v[140:141], v[130:133], off offset:256 nt
	s_cbranch_vccnz .LBB0_167
	s_nop 0
	v_mul_f32_e32 v130, 0xbfb8aa3b, v94
	v_mul_f32_e32 v131, 0xbfb8aa3b, v95
	v_mul_f32_e32 v132, 0xbfb8aa3b, v96
	v_mul_f32_e32 v133, 0xbfb8aa3b, v97
	v_mul_f32_e32 v134, 0xbfb8aa3b, v90
	v_mul_f32_e32 v135, 0xbfb8aa3b, v91
	v_mul_f32_e32 v136, 0xbfb8aa3b, v92
	v_mul_f32_e32 v137, 0xbfb8aa3b, v93
	v_exp_f32_e32 v130, v130
	v_exp_f32_e32 v131, v131
	v_exp_f32_e32 v132, v132
	v_exp_f32_e32 v133, v133
	v_exp_f32_e32 v134, v134
	v_exp_f32_e32 v135, v135
	v_exp_f32_e32 v136, v136
	v_exp_f32_e32 v137, v137
	v_add_f32_e32 v130, 1.0, v130
	v_add_f32_e32 v131, 1.0, v131
	v_add_f32_e32 v132, 1.0, v132
	v_add_f32_e32 v133, 1.0, v133
	v_add_f32_e32 v134, 1.0, v134
	v_add_f32_e32 v135, 1.0, v135
	v_add_f32_e32 v136, 1.0, v136
	v_add_f32_e32 v137, 1.0, v137
	v_rcp_f32_e32 v130, v130
	v_rcp_f32_e32 v131, v131
	v_rcp_f32_e32 v132, v132
	v_rcp_f32_e32 v133, v133
	v_rcp_f32_e32 v134, v134
	v_rcp_f32_e32 v136, v136
	v_rcp_f32_e32 v137, v137
	v_rcp_f32_e32 v135, v135
	v_pk_mul_f32 v[132:133], v[96:97], v[132:133]
	v_pk_mul_f32 v[130:131], v[94:95], v[130:131]
	v_pk_mul_f32 v[136:137], v[92:93], v[136:137]
	v_pk_mul_f32 v[134:135], v[90:91], v[134:135]
	s_mov_b64 s[12:13], 0

.LBB0_169:
	v_or_b32_e32 v140, 32, v208
	v_ashrrev_i32_e32 v141, 31, v140
	v_lshlrev_b64 v[140:141], 10, v[140:141]
	v_lshl_add_u64 v[140:141], v[138:139], 0, v[140:141]
	v_cvt_pk_bf16_f32 v130, v130, v131
	v_cvt_pk_bf16_f32 v131, v132, v133
	v_cvt_pk_bf16_f32 v132, v134, v135
	v_cvt_pk_bf16_f32 v133, v136, v137
	s_and_b64 vcc, exec, s[10:11]
	s_mov_b64 s[12:13], -1
	global_store_dwordx4 v[140:141], v[130:133], off nt
	s_cbranch_vccnz .LBB0_171
	s_nop 0
	v_mul_f32_e32 v130, 0xbfb8aa3b, v86
	v_mul_f32_e32 v131, 0xbfb8aa3b, v87
	v_mul_f32_e32 v132, 0xbfb8aa3b, v88
	v_mul_f32_e32 v133, 0xbfb8aa3b, v89
	v_mul_f32_e32 v134, 0xbfb8aa3b, v82
	v_mul_f32_e32 v135, 0xbfb8aa3b, v83
	v_mul_f32_e32 v136, 0xbfb8aa3b, v84
	v_mul_f32_e32 v137, 0xbfb8aa3b, v85
	v_exp_f32_e32 v130, v130
	v_exp_f32_e32 v131, v131
	v_exp_f32_e32 v132, v132
	v_exp_f32_e32 v133, v133
	v_exp_f32_e32 v134, v134
	v_exp_f32_e32 v135, v135
	v_exp_f32_e32 v136, v136
	v_exp_f32_e32 v137, v137
	v_add_f32_e32 v130, 1.0, v130
	v_add_f32_e32 v131, 1.0, v131
	v_add_f32_e32 v132, 1.0, v132
	v_add_f32_e32 v133, 1.0, v133
	v_add_f32_e32 v134, 1.0, v134
	v_add_f32_e32 v135, 1.0, v135
	v_add_f32_e32 v136, 1.0, v136
	v_add_f32_e32 v137, 1.0, v137
	v_rcp_f32_e32 v130, v130
	v_rcp_f32_e32 v131, v131
	v_rcp_f32_e32 v132, v132
	v_rcp_f32_e32 v133, v133
	v_rcp_f32_e32 v134, v134
	v_rcp_f32_e32 v136, v136
	v_rcp_f32_e32 v137, v137
	v_rcp_f32_e32 v135, v135
	v_pk_mul_f32 v[132:133], v[88:89], v[132:133]
	v_pk_mul_f32 v[130:131], v[86:87], v[130:131]
	v_pk_mul_f32 v[136:137], v[84:85], v[136:137]
	v_pk_mul_f32 v[134:135], v[82:83], v[134:135]
	s_mov_b64 s[12:13], 0

.LBB0_173:
	v_cvt_pk_bf16_f32 v130, v130, v131
	v_cvt_pk_bf16_f32 v131, v132, v133
	s_nop 0
	v_cvt_pk_bf16_f32 v132, v134, v135
	v_cvt_pk_bf16_f32 v133, v136, v137
	s_and_b64 vcc, exec, s[10:11]
	s_mov_b64 s[12:13], -1
	global_store_dwordx4 v[140:141], v[130:133], off offset:256 nt
	s_cbranch_vccnz .LBB0_175
	s_nop 0
	v_mul_f32_e32 v130, 0xbfb8aa3b, v78
	v_mul_f32_e32 v131, 0xbfb8aa3b, v79
	v_mul_f32_e32 v132, 0xbfb8aa3b, v80
	v_mul_f32_e32 v133, 0xbfb8aa3b, v81
	v_mul_f32_e32 v134, 0xbfb8aa3b, v74
	v_mul_f32_e32 v135, 0xbfb8aa3b, v75
	v_mul_f32_e32 v136, 0xbfb8aa3b, v76
	v_mul_f32_e32 v137, 0xbfb8aa3b, v77
	v_exp_f32_e32 v130, v130
	v_exp_f32_e32 v131, v131
	v_exp_f32_e32 v132, v132
	v_exp_f32_e32 v133, v133
	v_exp_f32_e32 v134, v134
	v_exp_f32_e32 v135, v135
	v_exp_f32_e32 v136, v136
	v_exp_f32_e32 v137, v137
	v_add_f32_e32 v130, 1.0, v130
	v_add_f32_e32 v131, 1.0, v131
	v_add_f32_e32 v132, 1.0, v132
	v_add_f32_e32 v133, 1.0, v133
	v_add_f32_e32 v134, 1.0, v134
	v_add_f32_e32 v135, 1.0, v135
	v_add_f32_e32 v136, 1.0, v136
	v_add_f32_e32 v137, 1.0, v137
	v_rcp_f32_e32 v130, v130
	v_rcp_f32_e32 v131, v131
	v_rcp_f32_e32 v132, v132
	v_rcp_f32_e32 v133, v133
	v_rcp_f32_e32 v134, v134
	v_rcp_f32_e32 v136, v136
	v_rcp_f32_e32 v137, v137
	v_rcp_f32_e32 v135, v135
	v_pk_mul_f32 v[132:133], v[80:81], v[132:133]
	v_pk_mul_f32 v[130:131], v[78:79], v[130:131]
	v_pk_mul_f32 v[136:137], v[76:77], v[136:137]
	v_pk_mul_f32 v[134:135], v[74:75], v[134:135]
	s_mov_b64 s[12:13], 0

.LBB0_177:
	v_or_b32_e32 v140, 48, v208
	v_ashrrev_i32_e32 v141, 31, v140
	v_lshlrev_b64 v[140:141], 10, v[140:141]
	v_lshl_add_u64 v[140:141], v[138:139], 0, v[140:141]
	v_cvt_pk_bf16_f32 v130, v130, v131
	v_cvt_pk_bf16_f32 v131, v132, v133
	v_cvt_pk_bf16_f32 v132, v134, v135
	v_cvt_pk_bf16_f32 v133, v136, v137
	s_and_b64 vcc, exec, s[10:11]
	s_mov_b64 s[12:13], -1
	global_store_dwordx4 v[140:141], v[130:133], off nt
	s_cbranch_vccnz .LBB0_179
	s_nop 0
	v_mul_f32_e32 v130, 0xbfb8aa3b, v70
	v_mul_f32_e32 v131, 0xbfb8aa3b, v71
	v_mul_f32_e32 v132, 0xbfb8aa3b, v72
	v_mul_f32_e32 v133, 0xbfb8aa3b, v73
	v_mul_f32_e32 v134, 0xbfb8aa3b, v66
	v_mul_f32_e32 v135, 0xbfb8aa3b, v67
	v_mul_f32_e32 v136, 0xbfb8aa3b, v68
	v_mul_f32_e32 v137, 0xbfb8aa3b, v69
	v_exp_f32_e32 v130, v130
	v_exp_f32_e32 v131, v131
	v_exp_f32_e32 v132, v132
	v_exp_f32_e32 v133, v133
	v_exp_f32_e32 v134, v134
	v_exp_f32_e32 v135, v135
	v_exp_f32_e32 v136, v136
	v_exp_f32_e32 v137, v137
	v_add_f32_e32 v130, 1.0, v130
	v_add_f32_e32 v131, 1.0, v131
	v_add_f32_e32 v132, 1.0, v132
	v_add_f32_e32 v133, 1.0, v133
	v_add_f32_e32 v134, 1.0, v134
	v_add_f32_e32 v135, 1.0, v135
	v_add_f32_e32 v136, 1.0, v136
	v_add_f32_e32 v137, 1.0, v137
	v_rcp_f32_e32 v130, v130
	v_rcp_f32_e32 v131, v131
	v_rcp_f32_e32 v132, v132
	v_rcp_f32_e32 v133, v133
	v_rcp_f32_e32 v134, v134
	v_rcp_f32_e32 v136, v136
	v_rcp_f32_e32 v137, v137
	v_rcp_f32_e32 v135, v135
	v_pk_mul_f32 v[132:133], v[72:73], v[132:133]
	v_pk_mul_f32 v[130:131], v[70:71], v[130:131]
	v_pk_mul_f32 v[136:137], v[68:69], v[136:137]
	v_pk_mul_f32 v[134:135], v[66:67], v[134:135]
	s_mov_b64 s[12:13], 0

.LBB0_181:
	v_cvt_pk_bf16_f32 v130, v130, v131
	v_cvt_pk_bf16_f32 v131, v132, v133
	s_nop 0
	v_cvt_pk_bf16_f32 v132, v134, v135
	v_cvt_pk_bf16_f32 v133, v136, v137
	s_and_b64 vcc, exec, s[10:11]
	s_mov_b64 s[12:13], -1
	global_store_dwordx4 v[140:141], v[130:133], off offset:256 nt
	s_cbranch_vccnz .LBB0_183
	s_nop 0
	v_mul_f32_e32 v130, 0xbfb8aa3b, v62
	v_mul_f32_e32 v131, 0xbfb8aa3b, v63
	v_mul_f32_e32 v132, 0xbfb8aa3b, v64
	v_mul_f32_e32 v133, 0xbfb8aa3b, v65
	v_mul_f32_e32 v134, 0xbfb8aa3b, v58
	v_mul_f32_e32 v135, 0xbfb8aa3b, v59
	v_mul_f32_e32 v136, 0xbfb8aa3b, v60
	v_mul_f32_e32 v137, 0xbfb8aa3b, v61
	v_exp_f32_e32 v130, v130
	v_exp_f32_e32 v131, v131
	v_exp_f32_e32 v132, v132
	v_exp_f32_e32 v133, v133
	v_exp_f32_e32 v134, v134
	v_exp_f32_e32 v135, v135
	v_exp_f32_e32 v136, v136
	v_exp_f32_e32 v137, v137
	v_add_f32_e32 v130, 1.0, v130
	v_add_f32_e32 v131, 1.0, v131
	v_add_f32_e32 v132, 1.0, v132
	v_add_f32_e32 v133, 1.0, v133
	v_add_f32_e32 v134, 1.0, v134
	v_add_f32_e32 v135, 1.0, v135
	v_add_f32_e32 v136, 1.0, v136
	v_add_f32_e32 v137, 1.0, v137
	v_rcp_f32_e32 v130, v130
	v_rcp_f32_e32 v131, v131
	v_rcp_f32_e32 v132, v132
	v_rcp_f32_e32 v133, v133
	v_rcp_f32_e32 v134, v134
	v_rcp_f32_e32 v136, v136
	v_rcp_f32_e32 v137, v137
	v_rcp_f32_e32 v135, v135
	v_pk_mul_f32 v[132:133], v[64:65], v[132:133]
	v_pk_mul_f32 v[130:131], v[62:63], v[130:131]
	v_pk_mul_f32 v[136:137], v[60:61], v[136:137]
	v_pk_mul_f32 v[134:135], v[58:59], v[134:135]
	s_mov_b64 s[12:13], 0

.LBB0_185:
	v_lshlrev_b64 v[140:141], 10, v[208:209]
	v_lshl_add_u64 v[140:141], v[138:139], 0, v[140:141]
	v_cvt_pk_bf16_f32 v130, v130, v131
	v_cvt_pk_bf16_f32 v131, v132, v133
	v_cvt_pk_bf16_f32 v132, v134, v135
	v_add_co_u32_e32 v134, vcc, 0x20000, v140
	v_cvt_pk_bf16_f32 v133, v136, v137
	s_mov_b64 s[12:13], -1
	s_nop 0
	v_addc_co_u32_e32 v135, vcc, 0, v141, vcc
	s_and_b64 vcc, exec, s[10:11]
	global_store_dwordx4 v[134:135], v[130:133], off nt
	s_cbranch_vccnz .LBB0_187
	s_nop 0
	v_mul_f32_e32 v130, 0xbfb8aa3b, v54
	v_mul_f32_e32 v131, 0xbfb8aa3b, v55
	v_mul_f32_e32 v132, 0xbfb8aa3b, v56
	v_mul_f32_e32 v133, 0xbfb8aa3b, v57
	v_mul_f32_e32 v134, 0xbfb8aa3b, v50
	v_mul_f32_e32 v135, 0xbfb8aa3b, v51
	v_mul_f32_e32 v136, 0xbfb8aa3b, v52
	v_mul_f32_e32 v137, 0xbfb8aa3b, v53
	v_exp_f32_e32 v130, v130
	v_exp_f32_e32 v131, v131
	v_exp_f32_e32 v132, v132
	v_exp_f32_e32 v133, v133
	v_exp_f32_e32 v134, v134
	v_exp_f32_e32 v135, v135
	v_exp_f32_e32 v136, v136
	v_exp_f32_e32 v137, v137
	v_add_f32_e32 v130, 1.0, v130
	v_add_f32_e32 v131, 1.0, v131
	v_add_f32_e32 v132, 1.0, v132
	v_add_f32_e32 v133, 1.0, v133
	v_add_f32_e32 v134, 1.0, v134
	v_add_f32_e32 v135, 1.0, v135
	v_add_f32_e32 v136, 1.0, v136
	v_add_f32_e32 v137, 1.0, v137
	v_rcp_f32_e32 v130, v130
	v_rcp_f32_e32 v131, v131
	v_rcp_f32_e32 v132, v132
	v_rcp_f32_e32 v133, v133
	v_rcp_f32_e32 v134, v134
	v_rcp_f32_e32 v136, v136
	v_rcp_f32_e32 v137, v137
	v_rcp_f32_e32 v135, v135
	v_pk_mul_f32 v[132:133], v[56:57], v[132:133]
	v_pk_mul_f32 v[130:131], v[54:55], v[130:131]
	v_pk_mul_f32 v[136:137], v[52:53], v[136:137]
	v_pk_mul_f32 v[134:135], v[50:51], v[134:135]
	s_mov_b64 s[12:13], 0

.LBB0_189:
	s_mov_b64 s[12:13], 0x20000
	v_lshl_add_u64 v[140:141], v[140:141], 0, s[12:13]
	v_cvt_pk_bf16_f32 v130, v130, v131
	v_cvt_pk_bf16_f32 v131, v132, v133
	v_cvt_pk_bf16_f32 v132, v134, v135
	v_cvt_pk_bf16_f32 v133, v136, v137
	s_and_b64 vcc, exec, s[10:11]
	s_mov_b64 s[12:13], -1
	global_store_dwordx4 v[140:141], v[130:133], off offset:256 nt
	s_cbranch_vccnz .LBB0_191
	s_nop 0
	v_mul_f32_e32 v130, 0xbfb8aa3b, v46
	v_mul_f32_e32 v131, 0xbfb8aa3b, v47
	v_mul_f32_e32 v132, 0xbfb8aa3b, v48
	v_mul_f32_e32 v133, 0xbfb8aa3b, v49
	v_mul_f32_e32 v134, 0xbfb8aa3b, v42
	v_mul_f32_e32 v135, 0xbfb8aa3b, v43
	v_mul_f32_e32 v136, 0xbfb8aa3b, v44
	v_mul_f32_e32 v137, 0xbfb8aa3b, v45
	v_exp_f32_e32 v130, v130
	v_exp_f32_e32 v131, v131
	v_exp_f32_e32 v132, v132
	v_exp_f32_e32 v133, v133
	v_exp_f32_e32 v134, v134
	v_exp_f32_e32 v135, v135
	v_exp_f32_e32 v136, v136
	v_exp_f32_e32 v137, v137
	v_add_f32_e32 v130, 1.0, v130
	v_add_f32_e32 v131, 1.0, v131
	v_add_f32_e32 v132, 1.0, v132
	v_add_f32_e32 v133, 1.0, v133
	v_add_f32_e32 v134, 1.0, v134
	v_add_f32_e32 v135, 1.0, v135
	v_add_f32_e32 v136, 1.0, v136
	v_add_f32_e32 v137, 1.0, v137
	v_rcp_f32_e32 v130, v130
	v_rcp_f32_e32 v131, v131
	v_rcp_f32_e32 v132, v132
	v_rcp_f32_e32 v133, v133
	v_rcp_f32_e32 v134, v134
	v_rcp_f32_e32 v136, v136
	v_rcp_f32_e32 v137, v137
	v_rcp_f32_e32 v135, v135
	v_pk_mul_f32 v[132:133], v[48:49], v[132:133]
	v_pk_mul_f32 v[130:131], v[46:47], v[130:131]
	v_pk_mul_f32 v[136:137], v[44:45], v[136:137]
	v_pk_mul_f32 v[134:135], v[42:43], v[134:135]
	s_mov_b64 s[12:13], 0

.LBB0_193:
	v_lshlrev_b64 v[140:141], 10, v[208:209]
	v_lshl_add_u64 v[140:141], v[138:139], 0, v[140:141]
	v_cvt_pk_bf16_f32 v130, v130, v131
	v_cvt_pk_bf16_f32 v131, v132, v133
	v_cvt_pk_bf16_f32 v132, v134, v135
	v_add_co_u32_e32 v134, vcc, 0x24000, v140
	v_cvt_pk_bf16_f32 v133, v136, v137
	s_mov_b64 s[12:13], -1
	s_nop 0
	v_addc_co_u32_e32 v135, vcc, 0, v141, vcc
	s_and_b64 vcc, exec, s[10:11]
	global_store_dwordx4 v[134:135], v[130:133], off nt
	s_cbranch_vccnz .LBB0_195
	s_nop 0
	v_mul_f32_e32 v130, 0xbfb8aa3b, v38
	v_mul_f32_e32 v131, 0xbfb8aa3b, v39
	v_mul_f32_e32 v132, 0xbfb8aa3b, v40
	v_mul_f32_e32 v133, 0xbfb8aa3b, v41
	v_mul_f32_e32 v134, 0xbfb8aa3b, v34
	v_mul_f32_e32 v135, 0xbfb8aa3b, v35
	v_mul_f32_e32 v136, 0xbfb8aa3b, v36
	v_mul_f32_e32 v137, 0xbfb8aa3b, v37
	v_exp_f32_e32 v130, v130
	v_exp_f32_e32 v131, v131
	v_exp_f32_e32 v132, v132
	v_exp_f32_e32 v133, v133
	v_exp_f32_e32 v134, v134
	v_exp_f32_e32 v135, v135
	v_exp_f32_e32 v136, v136
	v_exp_f32_e32 v137, v137
	v_add_f32_e32 v130, 1.0, v130
	v_add_f32_e32 v131, 1.0, v131
	v_add_f32_e32 v132, 1.0, v132
	v_add_f32_e32 v133, 1.0, v133
	v_add_f32_e32 v134, 1.0, v134
	v_add_f32_e32 v135, 1.0, v135
	v_add_f32_e32 v136, 1.0, v136
	v_add_f32_e32 v137, 1.0, v137
	v_rcp_f32_e32 v130, v130
	v_rcp_f32_e32 v131, v131
	v_rcp_f32_e32 v132, v132
	v_rcp_f32_e32 v133, v133
	v_rcp_f32_e32 v134, v134
	v_rcp_f32_e32 v136, v136
	v_rcp_f32_e32 v137, v137
	v_rcp_f32_e32 v135, v135
	v_pk_mul_f32 v[132:133], v[40:41], v[132:133]
	v_pk_mul_f32 v[130:131], v[38:39], v[130:131]
	v_pk_mul_f32 v[136:137], v[36:37], v[136:137]
	v_pk_mul_f32 v[134:135], v[34:35], v[134:135]
	s_mov_b64 s[12:13], 0

.LBB0_197:
	s_mov_b64 s[12:13], 0x24000
	v_lshl_add_u64 v[140:141], v[140:141], 0, s[12:13]
	v_cvt_pk_bf16_f32 v130, v130, v131
	v_cvt_pk_bf16_f32 v131, v132, v133
	v_cvt_pk_bf16_f32 v132, v134, v135
	v_cvt_pk_bf16_f32 v133, v136, v137
	s_and_b64 vcc, exec, s[10:11]
	s_mov_b64 s[12:13], -1
	global_store_dwordx4 v[140:141], v[130:133], off offset:256 nt
	s_cbranch_vccnz .LBB0_199
	s_nop 0
	v_mul_f32_e32 v130, 0xbfb8aa3b, v30
	v_mul_f32_e32 v131, 0xbfb8aa3b, v31
	v_mul_f32_e32 v132, 0xbfb8aa3b, v32
	v_mul_f32_e32 v133, 0xbfb8aa3b, v33
	v_mul_f32_e32 v134, 0xbfb8aa3b, v26
	v_mul_f32_e32 v135, 0xbfb8aa3b, v27
	v_mul_f32_e32 v136, 0xbfb8aa3b, v28
	v_mul_f32_e32 v137, 0xbfb8aa3b, v29
	v_exp_f32_e32 v130, v130
	v_exp_f32_e32 v131, v131
	v_exp_f32_e32 v132, v132
	v_exp_f32_e32 v133, v133
	v_exp_f32_e32 v134, v134
	v_exp_f32_e32 v135, v135
	v_exp_f32_e32 v136, v136
	v_exp_f32_e32 v137, v137
	v_add_f32_e32 v130, 1.0, v130
	v_add_f32_e32 v131, 1.0, v131
	v_add_f32_e32 v132, 1.0, v132
	v_add_f32_e32 v133, 1.0, v133
	v_add_f32_e32 v134, 1.0, v134
	v_add_f32_e32 v135, 1.0, v135
	v_add_f32_e32 v136, 1.0, v136
	v_add_f32_e32 v137, 1.0, v137
	v_rcp_f32_e32 v130, v130
	v_rcp_f32_e32 v131, v131
	v_rcp_f32_e32 v132, v132
	v_rcp_f32_e32 v133, v133
	v_rcp_f32_e32 v134, v134
	v_rcp_f32_e32 v136, v136
	v_rcp_f32_e32 v137, v137
	v_rcp_f32_e32 v135, v135
	v_pk_mul_f32 v[132:133], v[32:33], v[132:133]
	v_pk_mul_f32 v[130:131], v[30:31], v[130:131]
	v_pk_mul_f32 v[136:137], v[28:29], v[136:137]
	v_pk_mul_f32 v[134:135], v[26:27], v[134:135]
	s_mov_b64 s[12:13], 0

.LBB0_201:
	v_lshlrev_b64 v[140:141], 10, v[208:209]
	v_lshl_add_u64 v[140:141], v[138:139], 0, v[140:141]
	v_cvt_pk_bf16_f32 v130, v130, v131
	v_cvt_pk_bf16_f32 v131, v132, v133
	v_cvt_pk_bf16_f32 v132, v134, v135
	v_add_co_u32_e32 v134, vcc, 0x28000, v140
	v_cvt_pk_bf16_f32 v133, v136, v137
	s_mov_b64 s[12:13], -1
	s_nop 0
	v_addc_co_u32_e32 v135, vcc, 0, v141, vcc
	s_and_b64 vcc, exec, s[10:11]
	global_store_dwordx4 v[134:135], v[130:133], off nt
	s_cbranch_vccnz .LBB0_203
	s_nop 0
	v_mul_f32_e32 v130, 0xbfb8aa3b, v22
	v_mul_f32_e32 v131, 0xbfb8aa3b, v23
	v_mul_f32_e32 v132, 0xbfb8aa3b, v24
	v_mul_f32_e32 v133, 0xbfb8aa3b, v25
	v_mul_f32_e32 v134, 0xbfb8aa3b, v18
	v_mul_f32_e32 v135, 0xbfb8aa3b, v19
	v_mul_f32_e32 v136, 0xbfb8aa3b, v20
	v_mul_f32_e32 v137, 0xbfb8aa3b, v21
	v_exp_f32_e32 v130, v130
	v_exp_f32_e32 v131, v131
	v_exp_f32_e32 v132, v132
	v_exp_f32_e32 v133, v133
	v_exp_f32_e32 v134, v134
	v_exp_f32_e32 v135, v135
	v_exp_f32_e32 v136, v136
	v_exp_f32_e32 v137, v137
	v_add_f32_e32 v130, 1.0, v130
	v_add_f32_e32 v131, 1.0, v131
	v_add_f32_e32 v132, 1.0, v132
	v_add_f32_e32 v133, 1.0, v133
	v_add_f32_e32 v134, 1.0, v134
	v_add_f32_e32 v135, 1.0, v135
	v_add_f32_e32 v136, 1.0, v136
	v_add_f32_e32 v137, 1.0, v137
	v_rcp_f32_e32 v130, v130
	v_rcp_f32_e32 v131, v131
	v_rcp_f32_e32 v132, v132
	v_rcp_f32_e32 v133, v133
	v_rcp_f32_e32 v134, v134
	v_rcp_f32_e32 v136, v136
	v_rcp_f32_e32 v137, v137
	v_rcp_f32_e32 v135, v135
	v_pk_mul_f32 v[132:133], v[24:25], v[132:133]
	v_pk_mul_f32 v[130:131], v[22:23], v[130:131]
	v_pk_mul_f32 v[136:137], v[20:21], v[136:137]
	v_pk_mul_f32 v[134:135], v[18:19], v[134:135]
	s_mov_b64 s[12:13], 0

.LBB0_205:
	s_mov_b64 s[12:13], 0x28000
	v_lshl_add_u64 v[140:141], v[140:141], 0, s[12:13]
	v_cvt_pk_bf16_f32 v130, v130, v131
	v_cvt_pk_bf16_f32 v131, v132, v133
	v_cvt_pk_bf16_f32 v132, v134, v135
	v_cvt_pk_bf16_f32 v133, v136, v137
	s_and_b64 vcc, exec, s[10:11]
	s_mov_b64 s[12:13], -1
	global_store_dwordx4 v[140:141], v[130:133], off offset:256 nt
	s_cbranch_vccnz .LBB0_207
	s_nop 0
	v_mul_f32_e32 v130, 0xbfb8aa3b, v14
	v_mul_f32_e32 v131, 0xbfb8aa3b, v15
	v_mul_f32_e32 v132, 0xbfb8aa3b, v16
	v_mul_f32_e32 v133, 0xbfb8aa3b, v17
	v_mul_f32_e32 v134, 0xbfb8aa3b, v10
	v_mul_f32_e32 v135, 0xbfb8aa3b, v11
	v_mul_f32_e32 v136, 0xbfb8aa3b, v12
	v_mul_f32_e32 v137, 0xbfb8aa3b, v13
	v_exp_f32_e32 v130, v130
	v_exp_f32_e32 v131, v131
	v_exp_f32_e32 v132, v132
	v_exp_f32_e32 v133, v133
	v_exp_f32_e32 v134, v134
	v_exp_f32_e32 v135, v135
	v_exp_f32_e32 v136, v136
	v_exp_f32_e32 v137, v137
	v_add_f32_e32 v130, 1.0, v130
	v_add_f32_e32 v131, 1.0, v131
	v_add_f32_e32 v132, 1.0, v132
	v_add_f32_e32 v133, 1.0, v133
	v_add_f32_e32 v134, 1.0, v134
	v_add_f32_e32 v135, 1.0, v135
	v_add_f32_e32 v136, 1.0, v136
	v_add_f32_e32 v137, 1.0, v137
	v_rcp_f32_e32 v130, v130
	v_rcp_f32_e32 v131, v131
	v_rcp_f32_e32 v132, v132
	v_rcp_f32_e32 v133, v133
	v_rcp_f32_e32 v134, v134
	v_rcp_f32_e32 v136, v136
	v_rcp_f32_e32 v137, v137
	v_rcp_f32_e32 v135, v135
	v_pk_mul_f32 v[132:133], v[16:17], v[132:133]
	v_pk_mul_f32 v[130:131], v[14:15], v[130:131]
	v_pk_mul_f32 v[136:137], v[12:13], v[136:137]
	v_pk_mul_f32 v[134:135], v[10:11], v[134:135]
	s_mov_b64 s[12:13], 0

.LBB0_209:
	v_lshlrev_b64 v[140:141], 10, v[208:209]
	v_lshl_add_u64 v[138:139], v[138:139], 0, v[140:141]
	v_cvt_pk_bf16_f32 v130, v130, v131
	v_cvt_pk_bf16_f32 v131, v132, v133
	v_cvt_pk_bf16_f32 v132, v134, v135
	v_add_co_u32_e32 v134, vcc, 0x2c000, v138
	v_cvt_pk_bf16_f32 v133, v136, v137
	s_nop 1
	v_addc_co_u32_e32 v135, vcc, 0, v139, vcc
	s_and_b64 vcc, exec, s[10:11]
	s_mov_b64 s[10:11], -1
	global_store_dwordx4 v[134:135], v[130:133], off nt
	s_cbranch_vccnz .LBB0_211
	s_nop 0
	v_mul_f32_e32 v130, 0xbfb8aa3b, v6
	v_mul_f32_e32 v131, 0xbfb8aa3b, v7
	v_mul_f32_e32 v132, 0xbfb8aa3b, v8
	v_mul_f32_e32 v133, 0xbfb8aa3b, v9
	v_mul_f32_e32 v134, 0xbfb8aa3b, v2
	v_mul_f32_e32 v135, 0xbfb8aa3b, v3
	v_mul_f32_e32 v136, 0xbfb8aa3b, v4
	v_mul_f32_e32 v137, 0xbfb8aa3b, v5
	v_exp_f32_e32 v130, v130
	v_exp_f32_e32 v131, v131
	v_exp_f32_e32 v132, v132
	v_exp_f32_e32 v133, v133
	v_exp_f32_e32 v134, v134
	v_exp_f32_e32 v135, v135
	v_exp_f32_e32 v136, v136
	v_exp_f32_e32 v137, v137
	v_add_f32_e32 v130, 1.0, v130
	v_add_f32_e32 v131, 1.0, v131
	v_add_f32_e32 v132, 1.0, v132
	v_add_f32_e32 v133, 1.0, v133
	v_add_f32_e32 v134, 1.0, v134
	v_add_f32_e32 v135, 1.0, v135
	v_add_f32_e32 v136, 1.0, v136
	v_add_f32_e32 v137, 1.0, v137
	v_rcp_f32_e32 v130, v130
	v_rcp_f32_e32 v131, v131
	v_rcp_f32_e32 v132, v132
	v_rcp_f32_e32 v133, v133
	v_rcp_f32_e32 v134, v134
	v_rcp_f32_e32 v136, v136
	v_rcp_f32_e32 v137, v137
	v_rcp_f32_e32 v135, v135
	v_pk_mul_f32 v[132:133], v[8:9], v[132:133]
	v_pk_mul_f32 v[130:131], v[6:7], v[130:131]
	v_pk_mul_f32 v[136:137], v[4:5], v[136:137]
	v_pk_mul_f32 v[134:135], v[2:3], v[134:135]
	s_mov_b64 s[10:11], 0

.LBB0_213:
	s_mov_b64 s[10:11], 0x2c000
	v_lshl_add_u64 v[138:139], v[138:139], 0, s[10:11]
	v_cvt_pk_bf16_f32 v130, v130, v131
	v_cvt_pk_bf16_f32 v131, v132, v133
	v_cvt_pk_bf16_f32 v132, v134, v135
	v_cvt_pk_bf16_f32 v133, v136, v137
	global_store_dwordx4 v[138:139], v[130:133], off offset:256 nt
	s_mov_b64 s[10:11], 0

.LBB0_286:
	s_cmp_lg_u32 s24, 2
	v_ashrrev_i32_e32 v209, 31, v208
	s_cselect_b64 s[60:61], -1, 0
	s_and_b64 s[10:11], s[8:9], exec
	v_lshlrev_b64 v[212:213], 10, v[208:209]
	s_waitcnt vmcnt(0)
	v_pk_mul_f32 v[162:163], v[124:125], v[160:161]
	v_pk_mul_f32 v[216:217], v[122:123], v[158:159]
	s_cselect_b32 s62, s90, 0x8400000
	s_cselect_b32 s49, s91, 0x2100000
	s_cmp_eq_u32 s24, 2
	v_cmp_ne_u64_e64 s[12:13], 0, v[210:211]
	v_pk_fma_f32 v[164:165], v[128:129], v[156:157], v[162:163] neg_lo:[0,0,1] neg_hi:[0,0,1]
	v_pk_fma_f32 v[162:163], v[126:127], v[154:155], v[216:217] neg_lo:[0,0,1] neg_hi:[0,0,1]
	s_mov_b64 s[10:11], -1
	v_lshl_add_u64 v[212:213], s[30:31], 0, v[212:213]
	v_pk_mul_f32 v[216:217], v[126:127], v[158:159]
	v_lshlrev_b32_e32 v126, 1, v190
	s_cbranch_scc1 .LBB0_288
	s_lshl_b32 s10, s24, 8
	s_or_b32 s10, s10, s81
	s_ashr_i32 s11, s10, 31
	v_pk_mul_f32 v[234:235], v[128:129], v[160:161]
	v_lshl_add_u64 v[238:239], s[10:11], 1, v[212:213]
	v_mov_b32_e32 v127, v175
	v_pk_mul_f32 v[230:231], v[164:165], s[44:45] op_sel_hi:[1,0]
	v_pk_mul_f32 v[232:233], v[162:163], s[44:45] op_sel_hi:[1,0]
	v_pk_fma_f32 v[234:235], v[124:125], v[156:157], v[234:235]
	v_pk_fma_f32 v[236:237], v[122:123], v[154:155], v[216:217]
	v_lshl_add_u64 v[238:239], v[238:239], 0, v[126:127]
	s_mov_b64 s[10:11], 0
	v_pk_mul_f32 v[234:235], v[234:235], s[44:45] op_sel_hi:[1,0]
	v_pk_mul_f32 v[236:237], v[236:237], s[44:45] op_sel_hi:[1,0]
	v_cvt_pk_bf16_f32 v232, v232, v233
	v_cvt_pk_bf16_f32 v233, v230, v231
	global_store_dwordx2 v[238:239], v[232:233], off nt
	v_cvt_pk_bf16_f32 v230, v236, v237
	v_cvt_pk_bf16_f32 v231, v234, v235
	global_store_dwordx2 v[238:239], v[230:231], off offset:64 nt

.LBB0_292:
	s_and_b64 s[10:11], s[8:9], exec
	v_cndmask_b32_e64 v122, 0, 1, s[60:61]
	s_cselect_b32 s63, s92, 0x2140000
	s_cselect_b32 s94, s93, 0x8c00000
	v_cmp_ne_u32_e64 s[10:11], 1, v122
	s_andn2_b64 vcc, exec, s[60:61]
	s_mov_b64 s[60:61], -1
	s_cbranch_vccnz .LBB0_294
	s_lshl_b32 s26, s24, 8
	s_or_b32 s56, s26, s81
	v_pk_mul_f32 v[122:123], v[116:117], v[160:161]
	v_pk_mul_f32 v[124:125], v[114:115], v[158:159]
	v_pk_mul_f32 v[128:129], v[120:121], v[160:161]
	s_ashr_i32 s57, s56, 31
	v_pk_fma_f32 v[122:123], v[120:121], v[156:157], v[122:123] neg_lo:[0,0,1] neg_hi:[0,0,1]
	v_pk_fma_f32 v[124:125], v[118:119], v[154:155], v[124:125] neg_lo:[0,0,1] neg_hi:[0,0,1]
	v_pk_mul_f32 v[158:159], v[118:119], v[158:159]
	v_pk_fma_f32 v[128:129], v[116:117], v[156:157], v[128:129]
	v_lshl_add_u64 v[156:157], s[56:57], 1, v[212:213]
	v_mov_b32_e32 v127, v175
	v_pk_mul_f32 v[122:123], v[122:123], s[44:45] op_sel_hi:[1,0]
	v_pk_mul_f32 v[124:125], v[124:125], s[44:45] op_sel_hi:[1,0]
	v_pk_fma_f32 v[154:155], v[114:115], v[154:155], v[158:159]
	v_lshl_add_u64 v[156:157], v[156:157], 0, v[126:127]
	s_mov_b64 s[60:61], 0
	v_pk_mul_f32 v[128:129], v[128:129], s[44:45] op_sel_hi:[1,0]
	v_pk_mul_f32 v[154:155], v[154:155], s[44:45] op_sel_hi:[1,0]
	v_cvt_pk_bf16_f32 v124, v124, v125
	v_cvt_pk_bf16_f32 v125, v122, v123
	global_store_dwordx2 v[156:157], v[124:125], off offset:256 nt
	v_cvt_pk_bf16_f32 v122, v154, v155
	v_cvt_pk_bf16_f32 v123, v128, v129
	global_store_dwordx2 v[156:157], v[122:123], off offset:320 nt

.LBB0_302:
	v_or_b32_e32 v114, 16, v208
	v_ashrrev_i32_e32 v115, 31, v114
	v_lshlrev_b64 v[120:121], 10, v[114:115]
	v_pk_mul_f32 v[114:115], v[108:109], v[152:153]
	v_pk_mul_f32 v[124:125], v[106:107], v[150:151]
	v_cmp_ne_u64_e64 s[14:15], 0, v[118:119]
	v_pk_fma_f32 v[116:117], v[112:113], v[148:149], v[114:115] neg_lo:[0,0,1] neg_hi:[0,0,1]
	v_pk_fma_f32 v[114:115], v[110:111], v[146:147], v[124:125] neg_lo:[0,0,1] neg_hi:[0,0,1]
	s_mov_b64 s[60:61], -1
	s_and_b64 vcc, exec, s[10:11]
	v_lshl_add_u64 v[120:121], s[30:31], 0, v[120:121]
	v_pk_mul_f32 v[124:125], v[110:111], v[150:151]
	s_cbranch_vccnz .LBB0_308
	s_lshl_b32 s26, s24, 8
	s_or_b32 s56, s26, s81
	s_ashr_i32 s57, s56, 31
	v_pk_mul_f32 v[154:155], v[112:113], v[152:153]
	v_lshl_add_u64 v[158:159], s[56:57], 1, v[120:121]
	v_mov_b32_e32 v127, v175
	v_pk_mul_f32 v[110:111], v[116:117], s[44:45] op_sel_hi:[1,0]
	v_pk_mul_f32 v[128:129], v[114:115], s[44:45] op_sel_hi:[1,0]
	v_pk_fma_f32 v[154:155], v[108:109], v[148:149], v[154:155]
	v_pk_fma_f32 v[156:157], v[106:107], v[146:147], v[124:125]
	v_lshl_add_u64 v[158:159], v[158:159], 0, v[126:127]
	v_pk_mul_f32 v[154:155], v[154:155], s[44:45] op_sel_hi:[1,0]
	v_pk_mul_f32 v[156:157], v[156:157], s[44:45] op_sel_hi:[1,0]
	v_cvt_pk_bf16_f32 v128, v128, v129
	v_cvt_pk_bf16_f32 v129, v110, v111
	global_store_dwordx2 v[158:159], v[128:129], off nt
	v_cvt_pk_bf16_f32 v110, v156, v157
	v_cvt_pk_bf16_f32 v111, v154, v155
	global_store_dwordx2 v[158:159], v[110:111], off offset:64 nt
	v_ashrrev_i32_e32 v123, 31, v122
	v_lshlrev_b64 v[110:111], 12, v[122:123]
	s_cbranch_execz .LBB0_309

.LBB0_305:
	s_lshl_b32 s26, s24, 8
	s_or_b32 s56, s26, s81
	v_pk_mul_f32 v[106:107], v[100:101], v[152:153]
	v_pk_mul_f32 v[108:109], v[98:99], v[150:151]
	s_ashr_i32 s57, s56, 31
	v_pk_fma_f32 v[106:107], v[104:105], v[148:149], v[106:107] neg_lo:[0,0,1] neg_hi:[0,0,1]
	v_pk_fma_f32 v[108:109], v[102:103], v[146:147], v[108:109] neg_lo:[0,0,1] neg_hi:[0,0,1]
	v_pk_mul_f32 v[112:113], v[104:105], v[152:153]
	v_pk_mul_f32 v[114:115], v[102:103], v[150:151]
	v_lshl_add_u64 v[116:117], s[56:57], 1, v[120:121]
	v_mov_b32_e32 v127, v175
	v_pk_mul_f32 v[106:107], v[106:107], s[44:45] op_sel_hi:[1,0]
	v_pk_mul_f32 v[108:109], v[108:109], s[44:45] op_sel_hi:[1,0]
	v_pk_fma_f32 v[112:113], v[100:101], v[148:149], v[112:113]
	v_pk_fma_f32 v[114:115], v[98:99], v[146:147], v[114:115]
	v_lshl_add_u64 v[116:117], v[116:117], 0, v[126:127]
	v_pk_mul_f32 v[112:113], v[112:113], s[44:45] op_sel_hi:[1,0]
	v_pk_mul_f32 v[114:115], v[114:115], s[44:45] op_sel_hi:[1,0]
	v_cvt_pk_bf16_f32 v108, v108, v109
	v_cvt_pk_bf16_f32 v109, v106, v107
	global_store_dwordx2 v[116:117], v[108:109], off offset:256 nt
	v_cvt_pk_bf16_f32 v106, v114, v115
	v_cvt_pk_bf16_f32 v107, v112, v113
	global_store_dwordx2 v[116:117], v[106:107], off offset:320 nt
	s_cbranch_execz .LBB0_313

.LBB0_318:
	v_or_b32_e32 v98, 32, v208
	v_ashrrev_i32_e32 v99, 31, v98
	v_lshlrev_b64 v[104:105], 10, v[98:99]
	v_pk_mul_f32 v[98:99], v[92:93], v[144:145]
	v_pk_mul_f32 v[108:109], v[90:91], v[142:143]
	v_cmp_ne_u64_e64 s[14:15], 0, v[102:103]
	v_pk_fma_f32 v[100:101], v[96:97], v[140:141], v[98:99] neg_lo:[0,0,1] neg_hi:[0,0,1]
	v_pk_fma_f32 v[98:99], v[94:95], v[138:139], v[108:109] neg_lo:[0,0,1] neg_hi:[0,0,1]
	s_mov_b64 s[60:61], -1
	s_and_b64 vcc, exec, s[10:11]
	v_lshl_add_u64 v[104:105], s[30:31], 0, v[104:105]
	v_pk_mul_f32 v[108:109], v[94:95], v[142:143]
	s_cbranch_vccnz .LBB0_324
	s_lshl_b32 s26, s24, 8
	s_or_b32 s56, s26, s81
	s_ashr_i32 s57, s56, 31
	v_pk_mul_f32 v[112:113], v[96:97], v[144:145]
	v_lshl_add_u64 v[116:117], s[56:57], 1, v[104:105]
	v_mov_b32_e32 v127, v175
	v_pk_mul_f32 v[94:95], v[100:101], s[44:45] op_sel_hi:[1,0]
	v_pk_mul_f32 v[110:111], v[98:99], s[44:45] op_sel_hi:[1,0]
	v_pk_fma_f32 v[112:113], v[92:93], v[140:141], v[112:113]
	v_pk_fma_f32 v[114:115], v[90:91], v[138:139], v[108:109]
	v_lshl_add_u64 v[116:117], v[116:117], 0, v[126:127]
	v_pk_mul_f32 v[112:113], v[112:113], s[44:45] op_sel_hi:[1,0]
	v_pk_mul_f32 v[114:115], v[114:115], s[44:45] op_sel_hi:[1,0]
	v_cvt_pk_bf16_f32 v110, v110, v111
	v_cvt_pk_bf16_f32 v111, v94, v95
	global_store_dwordx2 v[116:117], v[110:111], off nt
	v_cvt_pk_bf16_f32 v94, v114, v115
	v_cvt_pk_bf16_f32 v95, v112, v113
	global_store_dwordx2 v[116:117], v[94:95], off offset:64 nt
	v_ashrrev_i32_e32 v107, 31, v106
	v_lshlrev_b64 v[94:95], 12, v[106:107]
	s_cbranch_execz .LBB0_325

.LBB0_321:
	s_lshl_b32 s26, s24, 8
	s_or_b32 s56, s26, s81
	v_pk_mul_f32 v[90:91], v[84:85], v[144:145]
	v_pk_mul_f32 v[92:93], v[82:83], v[142:143]
	s_ashr_i32 s57, s56, 31
	v_pk_fma_f32 v[90:91], v[88:89], v[140:141], v[90:91] neg_lo:[0,0,1] neg_hi:[0,0,1]
	v_pk_fma_f32 v[92:93], v[86:87], v[138:139], v[92:93] neg_lo:[0,0,1] neg_hi:[0,0,1]
	v_pk_mul_f32 v[96:97], v[88:89], v[144:145]
	v_pk_mul_f32 v[98:99], v[86:87], v[142:143]
	v_lshl_add_u64 v[100:101], s[56:57], 1, v[104:105]
	v_mov_b32_e32 v127, v175
	v_pk_mul_f32 v[90:91], v[90:91], s[44:45] op_sel_hi:[1,0]
	v_pk_mul_f32 v[92:93], v[92:93], s[44:45] op_sel_hi:[1,0]
	v_pk_fma_f32 v[96:97], v[84:85], v[140:141], v[96:97]
	v_pk_fma_f32 v[98:99], v[82:83], v[138:139], v[98:99]
	v_lshl_add_u64 v[100:101], v[100:101], 0, v[126:127]
	v_pk_mul_f32 v[96:97], v[96:97], s[44:45] op_sel_hi:[1,0]
	v_pk_mul_f32 v[98:99], v[98:99], s[44:45] op_sel_hi:[1,0]
	v_cvt_pk_bf16_f32 v92, v92, v93
	v_cvt_pk_bf16_f32 v93, v90, v91
	global_store_dwordx2 v[100:101], v[92:93], off offset:256 nt
	v_cvt_pk_bf16_f32 v90, v98, v99
	v_cvt_pk_bf16_f32 v91, v96, v97
	global_store_dwordx2 v[100:101], v[90:91], off offset:320 nt
	s_cbranch_execz .LBB0_329

.LBB0_334:
	v_or_b32_e32 v82, 48, v208
	v_ashrrev_i32_e32 v83, 31, v82
	v_lshlrev_b64 v[88:89], 10, v[82:83]
	v_pk_mul_f32 v[82:83], v[76:77], v[136:137]
	v_pk_mul_f32 v[92:93], v[74:75], v[134:135]
	v_cmp_ne_u64_e64 s[14:15], 0, v[86:87]
	v_pk_fma_f32 v[84:85], v[80:81], v[132:133], v[82:83] neg_lo:[0,0,1] neg_hi:[0,0,1]
	v_pk_fma_f32 v[82:83], v[78:79], v[130:131], v[92:93] neg_lo:[0,0,1] neg_hi:[0,0,1]
	s_mov_b64 s[60:61], -1
	s_and_b64 vcc, exec, s[10:11]
	v_lshl_add_u64 v[88:89], s[30:31], 0, v[88:89]
	v_pk_mul_f32 v[92:93], v[78:79], v[134:135]
	s_cbranch_vccnz .LBB0_338
	s_lshl_b32 s26, s24, 8
	s_or_b32 s56, s26, s81
	s_ashr_i32 s57, s56, 31
	v_pk_mul_f32 v[96:97], v[80:81], v[136:137]
	v_lshl_add_u64 v[100:101], s[56:57], 1, v[88:89]
	v_mov_b32_e32 v127, v175
	v_pk_mul_f32 v[78:79], v[84:85], s[44:45] op_sel_hi:[1,0]
	v_pk_mul_f32 v[94:95], v[82:83], s[44:45] op_sel_hi:[1,0]
	v_pk_fma_f32 v[96:97], v[76:77], v[132:133], v[96:97]
	v_pk_fma_f32 v[98:99], v[74:75], v[130:131], v[92:93]
	v_lshl_add_u64 v[100:101], v[100:101], 0, v[126:127]
	v_pk_mul_f32 v[96:97], v[96:97], s[44:45] op_sel_hi:[1,0]
	v_pk_mul_f32 v[98:99], v[98:99], s[44:45] op_sel_hi:[1,0]
	v_cvt_pk_bf16_f32 v94, v94, v95
	v_cvt_pk_bf16_f32 v95, v78, v79
	global_store_dwordx2 v[100:101], v[94:95], off nt
	v_cvt_pk_bf16_f32 v78, v98, v99
	v_cvt_pk_bf16_f32 v79, v96, v97
	global_store_dwordx2 v[100:101], v[78:79], off offset:64 nt
	v_ashrrev_i32_e32 v91, 31, v90
	v_lshlrev_b64 v[78:79], 12, v[90:91]
	s_cbranch_execz .LBB0_339

.LBB0_337:
	s_lshl_b32 s26, s24, 8
	s_or_b32 s56, s26, s81
	v_pk_mul_f32 v[74:75], v[68:69], v[136:137]
	v_pk_mul_f32 v[76:77], v[66:67], v[134:135]
	s_ashr_i32 s57, s56, 31
	v_pk_fma_f32 v[74:75], v[72:73], v[132:133], v[74:75] neg_lo:[0,0,1] neg_hi:[0,0,1]
	v_pk_fma_f32 v[76:77], v[70:71], v[130:131], v[76:77] neg_lo:[0,0,1] neg_hi:[0,0,1]
	v_pk_mul_f32 v[80:81], v[72:73], v[136:137]
	v_pk_mul_f32 v[82:83], v[70:71], v[134:135]
	v_lshl_add_u64 v[84:85], s[56:57], 1, v[88:89]
	v_mov_b32_e32 v127, v175
	v_pk_mul_f32 v[74:75], v[74:75], s[44:45] op_sel_hi:[1,0]
	v_pk_mul_f32 v[76:77], v[76:77], s[44:45] op_sel_hi:[1,0]
	v_pk_fma_f32 v[80:81], v[68:69], v[132:133], v[80:81]
	v_pk_fma_f32 v[82:83], v[66:67], v[130:131], v[82:83]
	v_lshl_add_u64 v[84:85], v[84:85], 0, v[126:127]
	v_pk_mul_f32 v[80:81], v[80:81], s[44:45] op_sel_hi:[1,0]
	v_pk_mul_f32 v[82:83], v[82:83], s[44:45] op_sel_hi:[1,0]
	v_cvt_pk_bf16_f32 v76, v76, v77
	v_cvt_pk_bf16_f32 v77, v74, v75
	global_store_dwordx2 v[84:85], v[76:77], off offset:256 nt
	v_cvt_pk_bf16_f32 v74, v82, v83
	v_cvt_pk_bf16_f32 v75, v80, v81
	global_store_dwordx2 v[84:85], v[74:75], off offset:320 nt
	s_cbranch_execnz .LBB0_346
	s_branch .LBB0_343

.LBB0_350:
	v_ashrrev_i32_e32 v99, 31, v98
	v_lshlrev_b64 v[110:111], 10, v[98:99]
	s_waitcnt vmcnt(6)
	v_pk_mul_f32 v[98:99], v[60:61], v[96:97]
	v_pk_mul_f32 v[114:115], v[58:59], v[94:95]
	v_cmp_ne_u64_e64 s[8:9], 0, v[108:109]
	v_pk_fma_f32 v[100:101], v[64:65], v[92:93], v[98:99] neg_lo:[0,0,1] neg_hi:[0,0,1]
	v_pk_fma_f32 v[98:99], v[62:63], v[90:91], v[114:115] neg_lo:[0,0,1] neg_hi:[0,0,1]
	s_mov_b64 s[14:15], -1
	s_and_b64 vcc, exec, s[10:11]
	v_lshl_add_u64 v[110:111], s[30:31], 0, v[110:111]
	v_pk_mul_f32 v[114:115], v[62:63], v[94:95]
	s_cbranch_vccnz .LBB0_356
	s_lshl_b32 s14, s24, 8
	s_or_b32 s14, s14, s81
	s_ashr_i32 s15, s14, 31
	v_pk_mul_f32 v[120:121], v[64:65], v[96:97]
	v_lshl_add_u64 v[124:125], s[14:15], 1, v[110:111]
	v_mov_b32_e32 v127, v175
	v_pk_mul_f32 v[62:63], v[100:101], s[44:45] op_sel_hi:[1,0]
	v_pk_mul_f32 v[118:119], v[98:99], s[44:45] op_sel_hi:[1,0]
	v_pk_fma_f32 v[120:121], v[60:61], v[92:93], v[120:121]
	v_pk_fma_f32 v[122:123], v[58:59], v[90:91], v[114:115]
	v_lshl_add_u64 v[124:125], v[124:125], 0, v[126:127]
	v_pk_mul_f32 v[120:121], v[120:121], s[44:45] op_sel_hi:[1,0]
	v_pk_mul_f32 v[122:123], v[122:123], s[44:45] op_sel_hi:[1,0]
	v_cvt_pk_bf16_f32 v118, v118, v119
	v_cvt_pk_bf16_f32 v119, v62, v63
	global_store_dwordx2 v[124:125], v[118:119], off nt
	v_cvt_pk_bf16_f32 v62, v122, v123
	v_cvt_pk_bf16_f32 v63, v120, v121
	global_store_dwordx2 v[124:125], v[62:63], off offset:64 nt
	v_ashrrev_i32_e32 v113, 31, v112
	v_lshlrev_b64 v[62:63], 12, v[112:113]
	s_cbranch_execz .LBB0_357

.LBB0_353:
	s_lshl_b32 s14, s24, 8
	s_or_b32 s14, s14, s81
	v_pk_mul_f32 v[58:59], v[52:53], v[96:97]
	v_pk_mul_f32 v[60:61], v[50:51], v[94:95]
	v_pk_mul_f32 v[64:65], v[56:57], v[96:97]
	s_ashr_i32 s15, s14, 31
	v_pk_fma_f32 v[58:59], v[56:57], v[92:93], v[58:59] neg_lo:[0,0,1] neg_hi:[0,0,1]
	v_pk_fma_f32 v[60:61], v[54:55], v[90:91], v[60:61] neg_lo:[0,0,1] neg_hi:[0,0,1]
	v_pk_mul_f32 v[94:95], v[54:55], v[94:95]
	v_pk_fma_f32 v[64:65], v[52:53], v[92:93], v[64:65]
	v_lshl_add_u64 v[92:93], s[14:15], 1, v[110:111]
	v_mov_b32_e32 v127, v175
	v_pk_mul_f32 v[58:59], v[58:59], s[44:45] op_sel_hi:[1,0]
	v_pk_mul_f32 v[60:61], v[60:61], s[44:45] op_sel_hi:[1,0]
	v_pk_fma_f32 v[90:91], v[50:51], v[90:91], v[94:95]
	v_lshl_add_u64 v[92:93], v[92:93], 0, v[126:127]
	v_pk_mul_f32 v[64:65], v[64:65], s[44:45] op_sel_hi:[1,0]
	v_pk_mul_f32 v[90:91], v[90:91], s[44:45] op_sel_hi:[1,0]
	v_cvt_pk_bf16_f32 v60, v60, v61
	v_cvt_pk_bf16_f32 v61, v58, v59
	global_store_dwordx2 v[92:93], v[60:61], off offset:256 nt
	v_cvt_pk_bf16_f32 v58, v90, v91
	v_cvt_pk_bf16_f32 v59, v64, v65
	global_store_dwordx2 v[92:93], v[58:59], off offset:320 nt
	s_cbranch_execz .LBB0_361

.LBB0_366:
	v_ashrrev_i32_e32 v107, 31, v106
	v_lshlrev_b64 v[56:57], 10, v[106:107]
	s_waitcnt vmcnt(4)
	v_pk_mul_f32 v[50:51], v[44:45], v[88:89]
	v_pk_mul_f32 v[60:61], v[42:43], v[86:87]
	v_cmp_ne_u64_e64 s[8:9], 0, v[54:55]
	v_pk_fma_f32 v[52:53], v[48:49], v[84:85], v[50:51] neg_lo:[0,0,1] neg_hi:[0,0,1]
	v_pk_fma_f32 v[50:51], v[46:47], v[82:83], v[60:61] neg_lo:[0,0,1] neg_hi:[0,0,1]
	s_mov_b64 s[14:15], -1
	s_and_b64 vcc, exec, s[10:11]
	v_lshl_add_u64 v[56:57], s[30:31], 0, v[56:57]
	v_pk_mul_f32 v[60:61], v[46:47], v[86:87]
	s_cbranch_vccnz .LBB0_372
	s_lshl_b32 s14, s24, 8
	s_or_b32 s14, s14, s81
	s_ashr_i32 s15, s14, 31
	v_pk_mul_f32 v[64:65], v[48:49], v[88:89]
	v_lshl_add_u64 v[92:93], s[14:15], 1, v[56:57]
	v_mov_b32_e32 v127, v175
	v_pk_mul_f32 v[46:47], v[52:53], s[44:45] op_sel_hi:[1,0]
	v_pk_mul_f32 v[62:63], v[50:51], s[44:45] op_sel_hi:[1,0]
	v_pk_fma_f32 v[64:65], v[44:45], v[84:85], v[64:65]
	v_pk_fma_f32 v[90:91], v[42:43], v[82:83], v[60:61]
	v_lshl_add_u64 v[92:93], v[92:93], 0, v[126:127]
	v_pk_mul_f32 v[64:65], v[64:65], s[44:45] op_sel_hi:[1,0]
	v_pk_mul_f32 v[90:91], v[90:91], s[44:45] op_sel_hi:[1,0]
	v_cvt_pk_bf16_f32 v62, v62, v63
	v_cvt_pk_bf16_f32 v63, v46, v47
	global_store_dwordx2 v[92:93], v[62:63], off nt
	v_cvt_pk_bf16_f32 v46, v90, v91
	v_cvt_pk_bf16_f32 v47, v64, v65
	global_store_dwordx2 v[92:93], v[46:47], off offset:64 nt
	v_ashrrev_i32_e32 v59, 31, v58
	v_lshlrev_b64 v[46:47], 12, v[58:59]
	s_cbranch_execz .LBB0_373

.LBB0_369:
	s_lshl_b32 s14, s24, 8
	s_or_b32 s14, s14, s81
	v_pk_mul_f32 v[42:43], v[36:37], v[88:89]
	v_pk_mul_f32 v[44:45], v[34:35], v[86:87]
	s_ashr_i32 s15, s14, 31
	v_pk_fma_f32 v[42:43], v[40:41], v[84:85], v[42:43] neg_lo:[0,0,1] neg_hi:[0,0,1]
	v_pk_fma_f32 v[44:45], v[38:39], v[82:83], v[44:45] neg_lo:[0,0,1] neg_hi:[0,0,1]
	v_pk_mul_f32 v[48:49], v[40:41], v[88:89]
	v_pk_mul_f32 v[50:51], v[38:39], v[86:87]
	v_lshl_add_u64 v[52:53], s[14:15], 1, v[56:57]
	v_mov_b32_e32 v127, v175
	v_pk_mul_f32 v[42:43], v[42:43], s[44:45] op_sel_hi:[1,0]
	v_pk_mul_f32 v[44:45], v[44:45], s[44:45] op_sel_hi:[1,0]
	v_pk_fma_f32 v[48:49], v[36:37], v[84:85], v[48:49]
	v_pk_fma_f32 v[50:51], v[34:35], v[82:83], v[50:51]
	v_lshl_add_u64 v[52:53], v[52:53], 0, v[126:127]
	v_pk_mul_f32 v[48:49], v[48:49], s[44:45] op_sel_hi:[1,0]
	v_pk_mul_f32 v[50:51], v[50:51], s[44:45] op_sel_hi:[1,0]
	v_cvt_pk_bf16_f32 v44, v44, v45
	v_cvt_pk_bf16_f32 v45, v42, v43
	global_store_dwordx2 v[52:53], v[44:45], off offset:256 nt
	v_cvt_pk_bf16_f32 v42, v50, v51
	v_cvt_pk_bf16_f32 v43, v48, v49
	global_store_dwordx2 v[52:53], v[42:43], off offset:320 nt
	s_cbranch_execz .LBB0_377

.LBB0_382:
	v_ashrrev_i32_e32 v105, 31, v104
	v_lshlrev_b64 v[40:41], 10, v[104:105]
	s_waitcnt vmcnt(2)
	v_pk_mul_f32 v[34:35], v[28:29], v[80:81]
	v_pk_mul_f32 v[44:45], v[26:27], v[78:79]
	v_cmp_ne_u64_e64 s[8:9], 0, v[38:39]
	v_pk_fma_f32 v[36:37], v[32:33], v[76:77], v[34:35] neg_lo:[0,0,1] neg_hi:[0,0,1]
	v_pk_fma_f32 v[34:35], v[30:31], v[74:75], v[44:45] neg_lo:[0,0,1] neg_hi:[0,0,1]
	s_mov_b64 s[14:15], -1
	s_and_b64 vcc, exec, s[10:11]
	v_lshl_add_u64 v[40:41], s[30:31], 0, v[40:41]
	v_pk_mul_f32 v[44:45], v[30:31], v[78:79]
	s_cbranch_vccnz .LBB0_388
	s_lshl_b32 s14, s24, 8
	s_or_b32 s14, s14, s81
	s_ashr_i32 s15, s14, 31
	v_pk_mul_f32 v[48:49], v[32:33], v[80:81]
	v_lshl_add_u64 v[52:53], s[14:15], 1, v[40:41]
	v_mov_b32_e32 v127, v175
	v_pk_mul_f32 v[30:31], v[36:37], s[44:45] op_sel_hi:[1,0]
	v_pk_mul_f32 v[46:47], v[34:35], s[44:45] op_sel_hi:[1,0]
	v_pk_fma_f32 v[48:49], v[28:29], v[76:77], v[48:49]
	v_pk_fma_f32 v[50:51], v[26:27], v[74:75], v[44:45]
	v_lshl_add_u64 v[52:53], v[52:53], 0, v[126:127]
	v_pk_mul_f32 v[48:49], v[48:49], s[44:45] op_sel_hi:[1,0]
	v_pk_mul_f32 v[50:51], v[50:51], s[44:45] op_sel_hi:[1,0]
	v_cvt_pk_bf16_f32 v46, v46, v47
	v_cvt_pk_bf16_f32 v47, v30, v31
	global_store_dwordx2 v[52:53], v[46:47], off nt
	v_cvt_pk_bf16_f32 v30, v50, v51
	v_cvt_pk_bf16_f32 v31, v48, v49
	global_store_dwordx2 v[52:53], v[30:31], off offset:64 nt
	v_ashrrev_i32_e32 v43, 31, v42
	v_lshlrev_b64 v[30:31], 12, v[42:43]
	s_cbranch_execz .LBB0_389

.LBB0_385:
	s_lshl_b32 s14, s24, 8
	s_or_b32 s14, s14, s81
	v_pk_mul_f32 v[26:27], v[20:21], v[80:81]
	v_pk_mul_f32 v[28:29], v[18:19], v[78:79]
	s_ashr_i32 s15, s14, 31
	v_pk_fma_f32 v[26:27], v[24:25], v[76:77], v[26:27] neg_lo:[0,0,1] neg_hi:[0,0,1]
	v_pk_fma_f32 v[28:29], v[22:23], v[74:75], v[28:29] neg_lo:[0,0,1] neg_hi:[0,0,1]
	v_pk_mul_f32 v[32:33], v[24:25], v[80:81]
	v_pk_mul_f32 v[34:35], v[22:23], v[78:79]
	v_lshl_add_u64 v[36:37], s[14:15], 1, v[40:41]
	v_mov_b32_e32 v127, v175
	v_pk_mul_f32 v[26:27], v[26:27], s[44:45] op_sel_hi:[1,0]
	v_pk_mul_f32 v[28:29], v[28:29], s[44:45] op_sel_hi:[1,0]
	v_pk_fma_f32 v[32:33], v[20:21], v[76:77], v[32:33]
	v_pk_fma_f32 v[34:35], v[18:19], v[74:75], v[34:35]
	v_lshl_add_u64 v[36:37], v[36:37], 0, v[126:127]
	v_pk_mul_f32 v[32:33], v[32:33], s[44:45] op_sel_hi:[1,0]
	v_pk_mul_f32 v[34:35], v[34:35], s[44:45] op_sel_hi:[1,0]
	v_cvt_pk_bf16_f32 v28, v28, v29
	v_cvt_pk_bf16_f32 v29, v26, v27
	global_store_dwordx2 v[36:37], v[28:29], off offset:256 nt
	v_cvt_pk_bf16_f32 v26, v34, v35
	v_cvt_pk_bf16_f32 v27, v32, v33
	global_store_dwordx2 v[36:37], v[26:27], off offset:320 nt
	s_cbranch_execz .LBB0_393

.LBB0_398:
	v_ashrrev_i32_e32 v103, 31, v102
	v_lshlrev_b64 v[24:25], 10, v[102:103]
	s_waitcnt vmcnt(0)
	v_pk_mul_f32 v[18:19], v[12:13], v[72:73]
	v_pk_mul_f32 v[28:29], v[10:11], v[70:71]
	v_cmp_ne_u64_e64 s[8:9], 0, v[22:23]
	v_pk_fma_f32 v[20:21], v[16:17], v[68:69], v[18:19] neg_lo:[0,0,1] neg_hi:[0,0,1]
	v_pk_fma_f32 v[18:19], v[14:15], v[66:67], v[28:29] neg_lo:[0,0,1] neg_hi:[0,0,1]
	s_mov_b64 s[12:13], -1
	s_and_b64 vcc, exec, s[10:11]
	v_lshl_add_u64 v[24:25], s[30:31], 0, v[24:25]
	v_pk_mul_f32 v[28:29], v[14:15], v[70:71]
	s_cbranch_vccnz .LBB0_405
	s_lshl_b32 s12, s24, 8
	s_or_b32 s12, s12, s81
	s_ashr_i32 s13, s12, 31
	v_pk_mul_f32 v[32:33], v[16:17], v[72:73]
	v_lshl_add_u64 v[36:37], s[12:13], 1, v[24:25]
	v_mov_b32_e32 v127, v175
	v_pk_mul_f32 v[14:15], v[20:21], s[44:45] op_sel_hi:[1,0]
	v_pk_mul_f32 v[30:31], v[18:19], s[44:45] op_sel_hi:[1,0]
	v_pk_fma_f32 v[32:33], v[12:13], v[68:69], v[32:33]
	v_pk_fma_f32 v[34:35], v[10:11], v[66:67], v[28:29]
	v_lshl_add_u64 v[36:37], v[36:37], 0, v[126:127]
	v_pk_mul_f32 v[32:33], v[32:33], s[44:45] op_sel_hi:[1,0]
	v_pk_mul_f32 v[34:35], v[34:35], s[44:45] op_sel_hi:[1,0]
	v_cvt_pk_bf16_f32 v30, v30, v31
	v_cvt_pk_bf16_f32 v31, v14, v15
	global_store_dwordx2 v[36:37], v[30:31], off nt
	v_cvt_pk_bf16_f32 v14, v34, v35
	v_cvt_pk_bf16_f32 v15, v32, v33
	global_store_dwordx2 v[36:37], v[14:15], off offset:64 nt
	v_ashrrev_i32_e32 v27, 31, v26
	v_lshlrev_b64 v[14:15], 12, v[26:27]
	s_cbranch_execz .LBB0_406

.LBB0_401:
	s_lshl_b32 s10, s24, 8
	s_or_b32 s10, s10, s81
	v_pk_mul_f32 v[10:11], v[4:5], v[72:73]
	v_pk_mul_f32 v[12:13], v[2:3], v[70:71]
	s_ashr_i32 s11, s10, 31
	v_pk_fma_f32 v[10:11], v[8:9], v[68:69], v[10:11] neg_lo:[0,0,1] neg_hi:[0,0,1]
	v_pk_fma_f32 v[12:13], v[6:7], v[66:67], v[12:13] neg_lo:[0,0,1] neg_hi:[0,0,1]
	v_pk_mul_f32 v[16:17], v[8:9], v[72:73]
	v_pk_mul_f32 v[18:19], v[6:7], v[70:71]
	v_lshl_add_u64 v[20:21], s[10:11], 1, v[24:25]
	v_mov_b32_e32 v127, v175
	v_pk_mul_f32 v[10:11], v[10:11], s[44:45] op_sel_hi:[1,0]
	v_pk_mul_f32 v[12:13], v[12:13], s[44:45] op_sel_hi:[1,0]
	v_pk_fma_f32 v[16:17], v[4:5], v[68:69], v[16:17]
	v_pk_fma_f32 v[18:19], v[2:3], v[66:67], v[18:19]
	v_lshl_add_u64 v[20:21], v[20:21], 0, v[126:127]
	v_pk_mul_f32 v[16:17], v[16:17], s[44:45] op_sel_hi:[1,0]
	v_pk_mul_f32 v[18:19], v[18:19], s[44:45] op_sel_hi:[1,0]
	v_cvt_pk_bf16_f32 v12, v12, v13
	v_cvt_pk_bf16_f32 v13, v10, v11
	global_store_dwordx2 v[20:21], v[12:13], off offset:256 nt
	v_cvt_pk_bf16_f32 v10, v18, v19
	v_cvt_pk_bf16_f32 v11, v16, v17
	global_store_dwordx2 v[20:21], v[10:11], off offset:320 nt
	s_cbranch_execz .LBB0_410
